# fox skip threshold 93 nats (exact: p<2^-134 rounds to 0 in bf16 P operand; bit-identical output), G1/G2 epilogues de-serialised
# baseline (speedup 1.0000x reference)
; __global__ void __launch_bounds__(512, 2) hymba_fwd(Args a) {
;     ...
;             if (tid < 64) {
;                 const float c0 = dst[64 * tid]; int lo = 0, hi = tid;
;                 while (lo < hi) { const int mid = (lo + hi) >> 1; if (dst[64 * mid + 63] - c0 <= att::FOX_SKIP_NATS) hi = mid; else lo = mid + 1; }
;                 jtlo[blockIdx.x * 64 + tid] = lo;
;             }
.LBB0_202:
	v_add_u32_e32 v3, v2, v4
	v_ashrrev_i32_e32 v3, 1, v3
	v_lshlrev_b32_e32 v6, 6, v3
	v_ashrrev_i32_e32 v7, 31, v6
	v_lshl_add_u64 v[6:7], v[6:7], 2, s[8:9]
	global_load_dword v5, v[6:7], off offset:252
	s_mov_b32 s0, 0x42ba0000
	v_add_u32_e32 v6, 1, v3
	s_waitcnt vmcnt(0)
	v_sub_f32_e32 v5, v5, v0
	v_cmp_nge_f32_e32 vcc, s0, v5
	s_nop 1
	v_cndmask_b32_e32 v4, v4, v6, vcc
	v_cndmask_b32_e32 v2, v3, v2, vcc
	v_cmp_ge_i32_e32 vcc, v4, v2
	s_or_b64 s[6:7], vcc, s[6:7]
	s_andn2_b64 exec, exec, s[6:7]
	s_cbranch_execnz .LBB0_202
	s_or_b64 exec, exec, s[6:7]
